# attn_b loops rewritten: running max folded into MFMA C operand, per-lane max test, deferred rescale (T=8)
# speedup vs baseline: 1.0609x; 1.0201x over previous
.LBB0_641:
	s_ashr_i32 s0, s5, 7
	s_mul_i32 s23, s0, 0x3e00000
	s_mul_hi_i32 s17, s0, 0x3e00000
	s_add_u32 s0, s2, s23
	s_addc_u32 s1, s4, s17
	s_lshl_b32 s8, s5, 8
	s_and_b32 s8, s8, 0xf00
	v_and_b32_e32 v32, 15, v2
	v_lshl_add_u32 v0, v0, 5, s8
	s_waitcnt lgkmcnt(0)
	v_or_b32_e32 v3, v0, v32
	v_mov_b64_e32 v[4:5], s[0:1]
	v_mad_i64_i32 v[6:7], s[0:1], v3, s65, v[4:5]
	s_lshl_b32 s0, s5, 3
	v_or_b32_e32 v3, 16, v3
	s_and_b32 s8, s0, 0x380
	v_mad_i64_i32 v[8:9], s[0:1], v3, s65, v[4:5]
	v_ashrrev_i32_e32 v3, 3, v2
	s_waitcnt lgkmcnt(0)
	v_bfe_u32 v33, v2, 4, 2
	v_lshl_add_u64 v[6:7], v[6:7], 0, s[8:9]
	s_mov_b64 s[12:13], 0x1000
	v_lshl_add_u64 v[8:9], v[8:9], 0, s[8:9]
	v_mad_i64_i32 v[4:5], s[0:1], v3, s65, v[4:5]
	v_lshl_add_u64 v[110:111], v[6:7], 0, s[12:13]
	v_lshlrev_b32_e32 v0, 4, v33
	v_lshl_add_u64 v[108:109], v[8:9], 0, s[12:13]
	s_and_b32 s0, s5, 64
	v_lshl_add_u64 v[6:7], v[110:111], 0, v[0:1]
	v_lshl_add_u64 v[28:29], v[108:109], 0, v[0:1]
	s_lshl_b32 s8, s0, 1
	v_lshlrev_b32_e32 v0, 4, v2
	v_and_b32_e32 v0, 0x70, v0
	v_lshl_add_u64 v[4:5], v[4:5], 0, s[8:9]
	v_lshl_add_u64 v[30:31], v[4:5], 0, v[0:1]
	v_add_co_u32_e32 v4, vcc, s71, v30
	v_lshlrev_b32_e32 v118, 2, v33
	s_nop 0
	v_addc_co_u32_e32 v5, vcc, 0, v31, vcc
	global_load_dwordx4 v[20:23], v[4:5], off offset:1024
	global_load_dwordx4 v[24:27], v[4:5], off offset:1280
	global_load_dwordx4 v[16:19], v[6:7], off
	global_load_dwordx4 v[8:11], v[6:7], off offset:64
	global_load_dwordx4 v[12:15], v[28:29], off
	s_nop 0
	global_load_dwordx4 v[4:7], v[28:29], off offset:64
	v_bfe_u32 v29, v2, 2, 2
	v_lshlrev_b32_e32 v28, 3, v2
	v_or_b32_e32 v29, v118, v29
	s_mov_b64 s[18:19], 0x1400
	v_lshlrev_b32_e32 v34, 3, v33
	v_mul_lo_u32 v35, v3, s40
	v_mul_u32_u24_e32 v32, 0x50, v32
	v_and_b32_e32 v28, 24, v28
	v_mul_u32_u24_e32 v29, 0xa0, v29
	v_lshl_add_u64 v[112:113], v[30:31], 0, s[18:19]
	s_mov_b64 s[18:19], 0x1500
	s_mov_b64 s[88:89], 0x1000
	s_mov_b64 s[0:1], -1
	v_lshlrev_b32_e32 v116, 1, v32
	v_add3_u32 v119, 0, v29, v28
	s_cmp_lt_i32 s30, 4
	v_add3_u32 v120, 0, v35, v0
	v_lshl_add_u64 v[114:115], v[30:31], 0, s[18:19]
	v_lshlrev_b32_e32 v0, 1, v34
	s_barrier
	s_waitcnt vmcnt(5)
	ds_write_b128 v120, v[20:23]
	s_waitcnt vmcnt(4)
	ds_write_b128 v120, v[24:27] offset:20480
	s_waitcnt lgkmcnt(0)
	s_barrier
	s_cbranch_scc1 .Lb_groupA
	s_waitcnt vmcnt(0)
	v_mov_b32_e32 v34, 0
	v_mov_b32_e32 v35, 0
	v_mov_b32_e32 v36, 0
	v_mov_b32_e32 v37, 0
	v_mov_b32_e32 v42, 0
	v_mov_b32_e32 v43, 0
	v_mov_b32_e32 v44, 0
	v_mov_b32_e32 v45, 0
	v_mov_b32_e32 v56, 0
	v_mov_b32_e32 v57, 0
	v_mov_b32_e32 v58, 0
	v_mov_b32_e32 v59, 0
	v_mov_b32_e32 v60, 0
	v_mov_b32_e32 v61, 0
	v_mov_b32_e32 v62, 0
	v_mov_b32_e32 v63, 0
	v_mov_b32_e32 v20, 0
	v_mov_b32_e32 v21, 0
	v_mov_b32_e32 v22, 0
	v_mov_b32_e32 v23, 0
	v_mov_b32_e32 v24, 0
	v_mov_b32_e32 v25, 0
	v_mov_b32_e32 v26, 0
	v_mov_b32_e32 v27, 0
	v_mov_b32_e32 v38, 0
	v_mov_b32_e32 v39, 0
	v_mov_b32_e32 v40, 0
	v_mov_b32_e32 v41, 0
	v_mov_b32_e32 v28, 0
	v_mov_b32_e32 v29, 0
	v_mov_b32_e32 v30, 0
	v_mov_b32_e32 v31, 0
	v_mov_b32_e32 v180, 0
	v_mov_b32_e32 v181, 0
	v_mov_b32_e32 v182, 0
	v_mov_b32_e32 v183, 0
	v_mov_b32_e32 v184, 0
	v_mov_b32_e32 v185, 0
	v_mov_b32_e32 v186, 0
	v_mov_b32_e32 v187, 0
	v_mov_b32_e32 v188, 0
	v_mov_b32_e32 v189, 0
	v_mov_b32_e32 v190, 0
	v_mov_b32_e32 v191, 0
	v_mov_b32_e32 v204, 0
	v_mov_b32_e32 v205, 0
	v_mov_b32_e32 v206, 0
	v_mov_b32_e32 v207, 0
	v_mov_b32_e32 v48, 0
	v_mov_b32_e32 v49, 0
	v_mov_b32_e32 v50, 0
	v_mov_b32_e32 v51, 0
	v_mov_b32_e32 v52, 0
	v_mov_b32_e32 v53, 0
	v_mov_b32_e32 v54, 0
	v_mov_b32_e32 v55, 0
	v_mov_b32_e32 v80, 0
	v_mov_b32_e32 v64, 0
	v_add_u32_e32 v75, v116, v0
	s_mov_b32 s20, 0
	s_mov_b32 s42, 0
	s_mov_b32 s43, 0
	s_mov_b32 s51, 10240
	s_mov_b32 s30, 0xf8000
	s_mov_b32 s66, 0xff800000
	v_mov_b32_e32 v88, 0xff800000
	v_mov_b32_e32 v89, 0xff800000
	v_mov_b32_e32 v90, 0xff800000
	v_mov_b32_e32 v91, 0xff800000
	v_mov_b32_e32 v92, 0xff800000
	v_mov_b32_e32 v93, 0xff800000
	v_mov_b32_e32 v94, 0xff800000
	v_mov_b32_e32 v95, 0xff800000
	v_mov_b32_e32 v96, 0xff800000
	v_mov_b32_e32 v97, 0xff800000
	v_mov_b32_e32 v98, 0xff800000
	v_mov_b32_e32 v99, 0xff800000
	v_mov_b32_e32 v100, 0xff800000
	v_mov_b32_e32 v101, 0xff800000
	v_mov_b32_e32 v102, 0xff800000
	v_mov_b32_e32 v103, 0xff800000
	v_mov_b32_e32 v104, 0xff800000
	v_mov_b32_e32 v105, 0xff800000
	v_mov_b32_e32 v106, 0xff800000
	v_mov_b32_e32 v107, 0xff800000
	v_mov_b32_e32 v168, 0xff800000
	v_mov_b32_e32 v169, 0xff800000
	v_mov_b32_e32 v170, 0xff800000
	v_mov_b32_e32 v171, 0xff800000
	v_mov_b32_e32 v172, 0xff800000
	v_mov_b32_e32 v173, 0xff800000
	v_mov_b32_e32 v174, 0xff800000
	v_mov_b32_e32 v175, 0xff800000
	v_mov_b32_e32 v176, 0xff800000
	v_mov_b32_e32 v177, 0xff800000
	v_mov_b32_e32 v178, 0xff800000
	v_mov_b32_e32 v179, 0xff800000
.Lb_loopB:
	s_and_b32 s8, s20, 1
	s_mul_i32 s32, s8, 10240
	s_xor_b32 s8, s8, 1
	s_mul_i32 s8, s8, 10240
	v_add_u32_e32 v71, s32, v75
	v_add_u32_e32 v73, s8, v120
	v_add_u32_e32 v72, s42, v119
	v_add_u32_e32 v74, s51, v120
	s_mov_b32 s19, 0
	s_mov_b32 s18, s30
	v_lshl_add_u64 v[208:209], v[112:113], 0, s[18:19]
	v_lshl_add_u64 v[212:213], v[114:115], 0, s[18:19]
	global_load_dwordx4 v[208:211], v[208:209], off
	global_load_dwordx4 v[212:215], v[212:213], off
	ds_read_b128 v[216:219], v71 offset:0
	ds_read_b128 v[220:223], v71 offset:64
	ds_read_b128 v[224:227], v71 offset:2560
	ds_read_b128 v[228:231], v71 offset:2624
	ds_read_b128 v[232:235], v71 offset:5120
	ds_read_b128 v[236:239], v71 offset:5184
	v_max3_f32 v67, v88, v89, v90
	v_max3_f32 v67, v67, v91, v92
	v_max3_f32 v67, v67, v93, v94
	v_max3_f32 v67, v67, v95, v96
	v_max3_f32 v67, v67, v97, v98
	v_max3_f32 v67, v67, v99, v100
	v_max3_f32 v67, v67, v101, v102
	v_max_f32_e32 v67, v67, v103
	v_cmp_lt_f32_e32 vcc, s66, v67
	s_cbranch_vccz .Lb_nr_B_0
	v_mov_b32_e32 v68, v67
	s_nop 1
	v_permlane16_swap_b32_e32 v67, v68
	v_max_f32_e32 v67, v67, v68
	v_mov_b32_e32 v68, v67
	s_nop 1
	v_permlane32_swap_b32_e32 v67, v68
	v_max_f32_e32 v67, v67, v68
	v_cmp_lt_f32_e32 vcc, s66, v67
	s_nop 1
	v_cndmask_b32_e32 v69, 0, v67, vcc
	v_sub_f32_e32 v70, 0, v69
	v_exp_f32_e32 v70, v70
	v_sub_f32_e32 v48, v48, v69
	v_sub_f32_e32 v49, v49, v69
	v_sub_f32_e32 v50, v50, v69
	v_sub_f32_e32 v51, v51, v69
	v_mul_f32_e32 v80, v80, v70
	v_mul_f32_e32 v34, v34, v70
	v_mul_f32_e32 v35, v35, v70
	v_mul_f32_e32 v36, v36, v70
	v_mul_f32_e32 v37, v37, v70
	v_mul_f32_e32 v42, v42, v70
	v_mul_f32_e32 v43, v43, v70
	v_mul_f32_e32 v44, v44, v70
	v_mul_f32_e32 v45, v45, v70
	v_mul_f32_e32 v56, v56, v70
	v_mul_f32_e32 v57, v57, v70
	v_mul_f32_e32 v58, v58, v70
	v_mul_f32_e32 v59, v59, v70
	v_mul_f32_e32 v60, v60, v70
	v_mul_f32_e32 v61, v61, v70
	v_mul_f32_e32 v62, v62, v70
	v_mul_f32_e32 v63, v63, v70
	v_sub_f32_e32 v88, v88, v69
	v_sub_f32_e32 v89, v89, v69
	v_sub_f32_e32 v90, v90, v69
	v_sub_f32_e32 v91, v91, v69
	v_sub_f32_e32 v92, v92, v69
	v_sub_f32_e32 v93, v93, v69
	v_sub_f32_e32 v94, v94, v69
	v_sub_f32_e32 v95, v95, v69
	v_sub_f32_e32 v96, v96, v69
	v_sub_f32_e32 v97, v97, v69
	v_sub_f32_e32 v98, v98, v69
	v_sub_f32_e32 v99, v99, v69
	v_sub_f32_e32 v100, v100, v69
	v_sub_f32_e32 v101, v101, v69
	v_sub_f32_e32 v102, v102, v69
	v_sub_f32_e32 v103, v103, v69
.Lb_nr_B_0:
	v_exp_f32_e32 v88, v88
	v_exp_f32_e32 v89, v89
	v_exp_f32_e32 v90, v90
	v_exp_f32_e32 v91, v91
	v_exp_f32_e32 v92, v92
	v_exp_f32_e32 v93, v93
	v_exp_f32_e32 v94, v94
	v_exp_f32_e32 v95, v95
	v_exp_f32_e32 v96, v96
	v_exp_f32_e32 v97, v97
	v_exp_f32_e32 v98, v98
	v_exp_f32_e32 v99, v99
	v_exp_f32_e32 v100, v100
	v_exp_f32_e32 v101, v101
	v_exp_f32_e32 v102, v102
	v_exp_f32_e32 v103, v103
	s_nop 0
	v_add_f32_e32 v67, v88, v89
	v_add_f32_e32 v67, v67, v90
	v_add_f32_e32 v67, v67, v91
	v_add_f32_e32 v67, v67, v92
	v_add_f32_e32 v67, v67, v93
	v_add_f32_e32 v67, v67, v94
	v_add_f32_e32 v67, v67, v95
	v_add_f32_e32 v67, v67, v96
	v_add_f32_e32 v67, v67, v97
	v_add_f32_e32 v67, v67, v98
	v_add_f32_e32 v67, v67, v99
	v_add_f32_e32 v67, v67, v100
	v_add_f32_e32 v67, v67, v101
	v_add_f32_e32 v67, v67, v102
	v_add_f32_e32 v67, v67, v103
	v_add_f32_e32 v80, v80, v67
	v_cvt_pk_bf16_f32 v180, v88, v89
	v_cvt_pk_bf16_f32 v181, v90, v91
	v_cvt_pk_bf16_f32 v182, v92, v93
	v_cvt_pk_bf16_f32 v183, v94, v95
	v_cvt_pk_bf16_f32 v188, v96, v97
	v_cvt_pk_bf16_f32 v189, v98, v99
	v_cvt_pk_bf16_f32 v190, v100, v101
	v_cvt_pk_bf16_f32 v191, v102, v103
	v_max3_f32 v67, v104, v105, v106
	v_max3_f32 v67, v67, v107, v168
	v_max3_f32 v67, v67, v169, v170
	v_max3_f32 v67, v67, v171, v172
	v_max3_f32 v67, v67, v173, v174
	v_max3_f32 v67, v67, v175, v176
	v_max3_f32 v67, v67, v177, v178
	v_max_f32_e32 v67, v67, v179
	v_cmp_lt_f32_e32 vcc, s66, v67
	s_cbranch_vccz .Lb_nr_B_1
	v_mov_b32_e32 v68, v67
	s_nop 1
	v_permlane16_swap_b32_e32 v67, v68
	v_max_f32_e32 v67, v67, v68
	v_mov_b32_e32 v68, v67
	s_nop 1
	v_permlane32_swap_b32_e32 v67, v68
	v_max_f32_e32 v67, v67, v68
	v_cmp_lt_f32_e32 vcc, s66, v67
	s_nop 1
	v_cndmask_b32_e32 v69, 0, v67, vcc
	v_sub_f32_e32 v70, 0, v69
	v_exp_f32_e32 v70, v70
	v_sub_f32_e32 v52, v52, v69
	v_sub_f32_e32 v53, v53, v69
	v_sub_f32_e32 v54, v54, v69
	v_sub_f32_e32 v55, v55, v69
	v_mul_f32_e32 v64, v64, v70
	v_mul_f32_e32 v20, v20, v70
	v_mul_f32_e32 v21, v21, v70
	v_mul_f32_e32 v22, v22, v70
	v_mul_f32_e32 v23, v23, v70
	v_mul_f32_e32 v24, v24, v70
	v_mul_f32_e32 v25, v25, v70
	v_mul_f32_e32 v26, v26, v70
	v_mul_f32_e32 v27, v27, v70
	v_mul_f32_e32 v38, v38, v70
	v_mul_f32_e32 v39, v39, v70
	v_mul_f32_e32 v40, v40, v70
	v_mul_f32_e32 v41, v41, v70
	v_mul_f32_e32 v28, v28, v70
	v_mul_f32_e32 v29, v29, v70
	v_mul_f32_e32 v30, v30, v70
	v_mul_f32_e32 v31, v31, v70
	v_sub_f32_e32 v104, v104, v69
	v_sub_f32_e32 v105, v105, v69
	v_sub_f32_e32 v106, v106, v69
	v_sub_f32_e32 v107, v107, v69
	v_sub_f32_e32 v168, v168, v69
	v_sub_f32_e32 v169, v169, v69
	v_sub_f32_e32 v170, v170, v69
	v_sub_f32_e32 v171, v171, v69
	v_sub_f32_e32 v172, v172, v69
	v_sub_f32_e32 v173, v173, v69
	v_sub_f32_e32 v174, v174, v69
	v_sub_f32_e32 v175, v175, v69
	v_sub_f32_e32 v176, v176, v69
	v_sub_f32_e32 v177, v177, v69
	v_sub_f32_e32 v178, v178, v69
	v_sub_f32_e32 v179, v179, v69
.Lb_nr_B_1:
	v_exp_f32_e32 v104, v104
	v_exp_f32_e32 v105, v105
	v_exp_f32_e32 v106, v106
	v_exp_f32_e32 v107, v107
	v_exp_f32_e32 v168, v168
	v_exp_f32_e32 v169, v169
	v_exp_f32_e32 v170, v170
	v_exp_f32_e32 v171, v171
	v_exp_f32_e32 v172, v172
	v_exp_f32_e32 v173, v173
	v_exp_f32_e32 v174, v174
	v_exp_f32_e32 v175, v175
	v_exp_f32_e32 v176, v176
	v_exp_f32_e32 v177, v177
	v_exp_f32_e32 v178, v178
	v_exp_f32_e32 v179, v179
	s_nop 0
	v_add_f32_e32 v67, v104, v105
	v_add_f32_e32 v67, v67, v106
	v_add_f32_e32 v67, v67, v107
	v_add_f32_e32 v67, v67, v168
	v_add_f32_e32 v67, v67, v169
	v_add_f32_e32 v67, v67, v170
	v_add_f32_e32 v67, v67, v171
	v_add_f32_e32 v67, v67, v172
	v_add_f32_e32 v67, v67, v173
	v_add_f32_e32 v67, v67, v174
	v_add_f32_e32 v67, v67, v175
	v_add_f32_e32 v67, v67, v176
	v_add_f32_e32 v67, v67, v177
	v_add_f32_e32 v67, v67, v178
	v_add_f32_e32 v67, v67, v179
	v_add_f32_e32 v64, v64, v67
	v_cvt_pk_bf16_f32 v184, v104, v105
	v_cvt_pk_bf16_f32 v185, v106, v107
	v_cvt_pk_bf16_f32 v186, v168, v169
	v_cvt_pk_bf16_f32 v187, v170, v171
	v_cvt_pk_bf16_f32 v204, v172, v173
	v_cvt_pk_bf16_f32 v205, v174, v175
	v_cvt_pk_bf16_f32 v206, v176, v177
	v_cvt_pk_bf16_f32 v207, v178, v179
	ds_read_b128 v[240:243], v71 offset:7680
	s_waitcnt lgkmcnt(6)
	v_mfma_f32_16x16x32_bf16 v[88:91], v[216:219], v[16:19], v[48:51]
	v_mfma_f32_16x16x32_bf16 v[104:107], v[216:219], v[12:15], v[52:55]
	ds_read_b128 v[244:247], v71 offset:7744
	s_waitcnt lgkmcnt(6)
	v_mfma_f32_16x16x32_bf16 v[88:91], v[220:223], v[8:11], v[88:91]
	v_mfma_f32_16x16x32_bf16 v[104:107], v[220:223], v[4:7], v[104:107]
	ds_read_b64_tr_b16 v[248:249], v72 offset:20480
	ds_read_b64_tr_b16 v[250:251], v72 offset:23040
	s_waitcnt lgkmcnt(7)
	v_mfma_f32_16x16x32_bf16 v[92:95], v[224:227], v[16:19], v[48:51]
	v_mfma_f32_16x16x32_bf16 v[168:171], v[224:227], v[12:15], v[52:55]
	ds_read_b64_tr_b16 v[216:217], v72 offset:20512
	ds_read_b64_tr_b16 v[218:219], v72 offset:23072
	s_waitcnt lgkmcnt(8)
	v_mfma_f32_16x16x32_bf16 v[92:95], v[228:231], v[8:11], v[92:95]
	v_mfma_f32_16x16x32_bf16 v[168:171], v[228:231], v[4:7], v[168:171]
	ds_read_b64_tr_b16 v[220:221], v72 offset:20544
	ds_read_b64_tr_b16 v[222:223], v72 offset:23104
	s_waitcnt lgkmcnt(9)
	v_mfma_f32_16x16x32_bf16 v[96:99], v[232:235], v[16:19], v[48:51]
	v_mfma_f32_16x16x32_bf16 v[172:175], v[232:235], v[12:15], v[52:55]
	ds_read_b64_tr_b16 v[224:225], v72 offset:20576
	ds_read_b64_tr_b16 v[226:227], v72 offset:23136
	s_waitcnt lgkmcnt(10)
	v_mfma_f32_16x16x32_bf16 v[96:99], v[236:239], v[8:11], v[96:99]
	v_mfma_f32_16x16x32_bf16 v[172:175], v[236:239], v[4:7], v[172:175]
	ds_read_b64_tr_b16 v[228:229], v72 offset:25600
	ds_read_b64_tr_b16 v[230:231], v72 offset:28160
	s_waitcnt lgkmcnt(11)
	v_mfma_f32_16x16x32_bf16 v[100:103], v[240:243], v[16:19], v[48:51]
	v_mfma_f32_16x16x32_bf16 v[176:179], v[240:243], v[12:15], v[52:55]
	ds_read_b64_tr_b16 v[232:233], v72 offset:25632
	ds_read_b64_tr_b16 v[234:235], v72 offset:28192
	s_waitcnt lgkmcnt(12)
	v_mfma_f32_16x16x32_bf16 v[100:103], v[244:247], v[8:11], v[100:103]
	v_mfma_f32_16x16x32_bf16 v[176:179], v[244:247], v[4:7], v[176:179]
	ds_read_b64_tr_b16 v[236:237], v72 offset:25664
	ds_read_b64_tr_b16 v[238:239], v72 offset:28224
	s_waitcnt lgkmcnt(12)
	v_mfma_f32_16x16x32_bf16 v[34:37], v[248:251], v[180:183], v[34:37]
	v_mfma_f32_16x16x32_bf16 v[20:23], v[248:251], v[184:187], v[20:23]
	ds_read_b64_tr_b16 v[240:241], v72 offset:25696
	ds_read_b64_tr_b16 v[242:243], v72 offset:28256
	s_waitcnt lgkmcnt(12)
	v_mfma_f32_16x16x32_bf16 v[42:45], v[216:219], v[180:183], v[42:45]
	v_mfma_f32_16x16x32_bf16 v[24:27], v[216:219], v[184:187], v[24:27]
	s_waitcnt lgkmcnt(10)
	v_mfma_f32_16x16x32_bf16 v[56:59], v[220:223], v[180:183], v[56:59]
	v_mfma_f32_16x16x32_bf16 v[38:41], v[220:223], v[184:187], v[38:41]
	s_waitcnt lgkmcnt(8)
	v_mfma_f32_16x16x32_bf16 v[60:63], v[224:227], v[180:183], v[60:63]
	v_mfma_f32_16x16x32_bf16 v[28:31], v[224:227], v[184:187], v[28:31]
	s_waitcnt lgkmcnt(6)
	v_mfma_f32_16x16x32_bf16 v[34:37], v[228:231], v[188:191], v[34:37]
	v_mfma_f32_16x16x32_bf16 v[20:23], v[228:231], v[204:207], v[20:23]
	s_waitcnt lgkmcnt(4)
	v_mfma_f32_16x16x32_bf16 v[42:45], v[232:235], v[188:191], v[42:45]
	v_mfma_f32_16x16x32_bf16 v[24:27], v[232:235], v[204:207], v[24:27]
	s_waitcnt lgkmcnt(2)
	v_mfma_f32_16x16x32_bf16 v[56:59], v[236:239], v[188:191], v[56:59]
	v_mfma_f32_16x16x32_bf16 v[38:41], v[236:239], v[204:207], v[38:41]
	s_waitcnt lgkmcnt(0)
	v_mfma_f32_16x16x32_bf16 v[60:63], v[240:243], v[188:191], v[60:63]
	v_mfma_f32_16x16x32_bf16 v[28:31], v[240:243], v[204:207], v[28:31]
	s_waitcnt vmcnt(0)
	ds_write_b128 v73, v[208:211]
	ds_write_b128 v74, v[212:215] offset:20480
	s_mov_b32 s42, s43
	s_mov_b32 s43, s51
	s_add_i32 s51, s51, 10240
	s_cmp_lg_u32 s51, 30720
	s_cselect_b32 s51, s51, 0
	s_mov_b32 s66, 0xff800000
	s_cmp_ge_u32 s20, 1
	s_cselect_b32 s66, 0x41000000, s66
	s_add_i32 s20, s20, 1
	s_min_u32 s8, s20, 62
	s_add_i32 s8, s8, 1
	s_mul_i32 s30, s8, 0xf8000
	s_waitcnt lgkmcnt(0)
	s_barrier
	s_cmp_lt_u32 s20, 64
	s_cbranch_scc1 .Lb_loopB
	v_add_u32_e32 v72, s42, v119
	ds_read_b64_tr_b16 v[216:217], v72 offset:20480
	ds_read_b64_tr_b16 v[218:219], v72 offset:23040
	ds_read_b64_tr_b16 v[220:221], v72 offset:20512
	ds_read_b64_tr_b16 v[222:223], v72 offset:23072
	ds_read_b64_tr_b16 v[224:225], v72 offset:20544
	ds_read_b64_tr_b16 v[226:227], v72 offset:23104
	ds_read_b64_tr_b16 v[228:229], v72 offset:20576
	ds_read_b64_tr_b16 v[230:231], v72 offset:23136
	ds_read_b64_tr_b16 v[232:233], v72 offset:25600
	ds_read_b64_tr_b16 v[234:235], v72 offset:28160
	ds_read_b64_tr_b16 v[236:237], v72 offset:25632
	ds_read_b64_tr_b16 v[238:239], v72 offset:28192
	v_max3_f32 v67, v88, v89, v90
	v_max3_f32 v67, v67, v91, v92
	v_max3_f32 v67, v67, v93, v94
	v_max3_f32 v67, v67, v95, v96
	v_max3_f32 v67, v67, v97, v98
	v_max3_f32 v67, v67, v99, v100
	v_max3_f32 v67, v67, v101, v102
	v_max_f32_e32 v67, v67, v103
	v_cmp_lt_f32_e32 vcc, s66, v67
	s_cbranch_vccz .Lb_nr_Bt_0
	v_mov_b32_e32 v68, v67
	s_nop 1
	v_permlane16_swap_b32_e32 v67, v68
	v_max_f32_e32 v67, v67, v68
	v_mov_b32_e32 v68, v67
	s_nop 1
	v_permlane32_swap_b32_e32 v67, v68
	v_max_f32_e32 v67, v67, v68
	v_cmp_lt_f32_e32 vcc, s66, v67
	s_nop 1
	v_cndmask_b32_e32 v69, 0, v67, vcc
	v_sub_f32_e32 v70, 0, v69
	v_exp_f32_e32 v70, v70
	v_sub_f32_e32 v48, v48, v69
	v_sub_f32_e32 v49, v49, v69
	v_sub_f32_e32 v50, v50, v69
	v_sub_f32_e32 v51, v51, v69
	v_mul_f32_e32 v80, v80, v70
	v_mul_f32_e32 v34, v34, v70
	v_mul_f32_e32 v35, v35, v70
	v_mul_f32_e32 v36, v36, v70
	v_mul_f32_e32 v37, v37, v70
	v_mul_f32_e32 v42, v42, v70
	v_mul_f32_e32 v43, v43, v70
	v_mul_f32_e32 v44, v44, v70
	v_mul_f32_e32 v45, v45, v70
	v_mul_f32_e32 v56, v56, v70
	v_mul_f32_e32 v57, v57, v70
	v_mul_f32_e32 v58, v58, v70
	v_mul_f32_e32 v59, v59, v70
	v_mul_f32_e32 v60, v60, v70
	v_mul_f32_e32 v61, v61, v70
	v_mul_f32_e32 v62, v62, v70
	v_mul_f32_e32 v63, v63, v70
	v_sub_f32_e32 v88, v88, v69
	v_sub_f32_e32 v89, v89, v69
	v_sub_f32_e32 v90, v90, v69
	v_sub_f32_e32 v91, v91, v69
	v_sub_f32_e32 v92, v92, v69
	v_sub_f32_e32 v93, v93, v69
	v_sub_f32_e32 v94, v94, v69
	v_sub_f32_e32 v95, v95, v69
	v_sub_f32_e32 v96, v96, v69
	v_sub_f32_e32 v97, v97, v69
	v_sub_f32_e32 v98, v98, v69
	v_sub_f32_e32 v99, v99, v69
	v_sub_f32_e32 v100, v100, v69
	v_sub_f32_e32 v101, v101, v69
	v_sub_f32_e32 v102, v102, v69
	v_sub_f32_e32 v103, v103, v69

.Lb_nr_Bt_1:
	v_exp_f32_e32 v104, v104
	v_exp_f32_e32 v105, v105
	v_exp_f32_e32 v106, v106
	v_exp_f32_e32 v107, v107
	v_exp_f32_e32 v168, v168
	v_exp_f32_e32 v169, v169
	v_exp_f32_e32 v170, v170
	v_exp_f32_e32 v171, v171
	v_exp_f32_e32 v172, v172
	v_exp_f32_e32 v173, v173
	v_exp_f32_e32 v174, v174
	v_exp_f32_e32 v175, v175
	v_exp_f32_e32 v176, v176
	v_exp_f32_e32 v177, v177
	v_exp_f32_e32 v178, v178
	v_exp_f32_e32 v179, v179
	s_nop 0
	v_add_f32_e32 v67, v104, v105
	v_add_f32_e32 v67, v67, v106
	v_add_f32_e32 v67, v67, v107
	v_add_f32_e32 v67, v67, v168
	v_add_f32_e32 v67, v67, v169
	v_add_f32_e32 v67, v67, v170
	v_add_f32_e32 v67, v67, v171
	v_add_f32_e32 v67, v67, v172
	v_add_f32_e32 v67, v67, v173
	v_add_f32_e32 v67, v67, v174
	v_add_f32_e32 v67, v67, v175
	v_add_f32_e32 v67, v67, v176
	v_add_f32_e32 v67, v67, v177
	v_add_f32_e32 v67, v67, v178
	v_add_f32_e32 v67, v67, v179
	v_add_f32_e32 v64, v64, v67
	v_cvt_pk_bf16_f32 v184, v104, v105
	v_cvt_pk_bf16_f32 v185, v106, v107
	v_cvt_pk_bf16_f32 v186, v168, v169
	v_cvt_pk_bf16_f32 v187, v170, v171
	v_cvt_pk_bf16_f32 v204, v172, v173
	v_cvt_pk_bf16_f32 v205, v174, v175
	v_cvt_pk_bf16_f32 v206, v176, v177
	v_cvt_pk_bf16_f32 v207, v178, v179
	ds_read_b64_tr_b16 v[240:241], v72 offset:25664
	ds_read_b64_tr_b16 v[242:243], v72 offset:28224
	s_waitcnt lgkmcnt(12)
	v_mfma_f32_16x16x32_bf16 v[34:37], v[216:219], v[180:183], v[34:37]
	v_mfma_f32_16x16x32_bf16 v[20:23], v[216:219], v[184:187], v[20:23]
	ds_read_b64_tr_b16 v[244:245], v72 offset:25696
	ds_read_b64_tr_b16 v[246:247], v72 offset:28256
	s_waitcnt lgkmcnt(12)
	v_mfma_f32_16x16x32_bf16 v[42:45], v[220:223], v[180:183], v[42:45]
	v_mfma_f32_16x16x32_bf16 v[24:27], v[220:223], v[184:187], v[24:27]
	s_waitcnt lgkmcnt(10)
	v_mfma_f32_16x16x32_bf16 v[56:59], v[224:227], v[180:183], v[56:59]
	v_mfma_f32_16x16x32_bf16 v[38:41], v[224:227], v[184:187], v[38:41]
	s_waitcnt lgkmcnt(8)
	v_mfma_f32_16x16x32_bf16 v[60:63], v[228:231], v[180:183], v[60:63]
	v_mfma_f32_16x16x32_bf16 v[28:31], v[228:231], v[184:187], v[28:31]
	s_waitcnt lgkmcnt(6)
	v_mfma_f32_16x16x32_bf16 v[34:37], v[232:235], v[188:191], v[34:37]
	v_mfma_f32_16x16x32_bf16 v[20:23], v[232:235], v[204:207], v[20:23]
	s_waitcnt lgkmcnt(4)
	v_mfma_f32_16x16x32_bf16 v[42:45], v[236:239], v[188:191], v[42:45]
	v_mfma_f32_16x16x32_bf16 v[24:27], v[236:239], v[204:207], v[24:27]
	s_waitcnt lgkmcnt(2)
	v_mfma_f32_16x16x32_bf16 v[56:59], v[240:243], v[188:191], v[56:59]
	v_mfma_f32_16x16x32_bf16 v[38:41], v[240:243], v[204:207], v[38:41]
	s_waitcnt lgkmcnt(0)
	v_mfma_f32_16x16x32_bf16 v[60:63], v[244:247], v[188:191], v[60:63]
	v_mfma_f32_16x16x32_bf16 v[28:31], v[244:247], v[204:207], v[28:31]
	s_branch .LBB0_666
.Lb_groupA:
	s_waitcnt vmcnt(0)
	v_mov_b32_e32 v34, 0
	v_mov_b32_e32 v35, 0
	v_mov_b32_e32 v36, 0
	v_mov_b32_e32 v37, 0
	v_mov_b32_e32 v42, 0
	v_mov_b32_e32 v43, 0
	v_mov_b32_e32 v44, 0
	v_mov_b32_e32 v45, 0
	v_mov_b32_e32 v56, 0
	v_mov_b32_e32 v57, 0
	v_mov_b32_e32 v58, 0
	v_mov_b32_e32 v59, 0
	v_mov_b32_e32 v60, 0
	v_mov_b32_e32 v61, 0
	v_mov_b32_e32 v62, 0
	v_mov_b32_e32 v63, 0
	v_mov_b32_e32 v20, 0
	v_mov_b32_e32 v21, 0
	v_mov_b32_e32 v22, 0
	v_mov_b32_e32 v23, 0
	v_mov_b32_e32 v24, 0
	v_mov_b32_e32 v25, 0
	v_mov_b32_e32 v26, 0
	v_mov_b32_e32 v27, 0
	v_mov_b32_e32 v38, 0
	v_mov_b32_e32 v39, 0
	v_mov_b32_e32 v40, 0
	v_mov_b32_e32 v41, 0
	v_mov_b32_e32 v28, 0
	v_mov_b32_e32 v29, 0
	v_mov_b32_e32 v30, 0
	v_mov_b32_e32 v31, 0
	v_mov_b32_e32 v180, 0
	v_mov_b32_e32 v181, 0
	v_mov_b32_e32 v182, 0
	v_mov_b32_e32 v183, 0
	v_mov_b32_e32 v184, 0
	v_mov_b32_e32 v185, 0
	v_mov_b32_e32 v186, 0
	v_mov_b32_e32 v187, 0
	v_mov_b32_e32 v188, 0
	v_mov_b32_e32 v189, 0
	v_mov_b32_e32 v190, 0
	v_mov_b32_e32 v191, 0
	v_mov_b32_e32 v204, 0
	v_mov_b32_e32 v205, 0
	v_mov_b32_e32 v206, 0
	v_mov_b32_e32 v207, 0
	v_mov_b32_e32 v48, 0
	v_mov_b32_e32 v49, 0
	v_mov_b32_e32 v50, 0
	v_mov_b32_e32 v51, 0
	v_mov_b32_e32 v52, 0
	v_mov_b32_e32 v53, 0
	v_mov_b32_e32 v54, 0
	v_mov_b32_e32 v55, 0
	v_mov_b32_e32 v80, 0
	v_mov_b32_e32 v64, 0
	v_add_u32_e32 v75, v116, v0
	s_mov_b32 s20, 0
	s_mov_b32 s42, 0
	s_mov_b32 s43, 0
	s_mov_b32 s51, 10240
	s_mov_b32 s30, 0xf8000
	s_mov_b32 s66, 0xff800000
.Lb_loopA:
	s_and_b32 s8, s20, 1
	s_mul_i32 s32, s8, 10240
	s_xor_b32 s8, s8, 1
	s_mul_i32 s8, s8, 10240
	v_add_u32_e32 v71, s32, v75
	v_add_u32_e32 v73, s8, v120
	v_add_u32_e32 v72, s42, v119
	v_add_u32_e32 v74, s51, v120
	s_mov_b32 s19, 0
	s_mov_b32 s18, s30
	v_lshl_add_u64 v[208:209], v[112:113], 0, s[18:19]
	v_lshl_add_u64 v[212:213], v[114:115], 0, s[18:19]
	global_load_dwordx4 v[208:211], v[208:209], off
	global_load_dwordx4 v[212:215], v[212:213], off
	ds_read_b64_tr_b16 v[216:217], v72 offset:20480
	ds_read_b64_tr_b16 v[218:219], v72 offset:23040
	ds_read_b64_tr_b16 v[220:221], v72 offset:20512
	ds_read_b64_tr_b16 v[222:223], v72 offset:23072
	ds_read_b64_tr_b16 v[224:225], v72 offset:20544
	ds_read_b64_tr_b16 v[226:227], v72 offset:23104
	ds_read_b64_tr_b16 v[228:229], v72 offset:20576
	ds_read_b64_tr_b16 v[230:231], v72 offset:23136
	ds_read_b64_tr_b16 v[232:233], v72 offset:25600
	ds_read_b64_tr_b16 v[234:235], v72 offset:28160
	ds_read_b64_tr_b16 v[236:237], v72 offset:25632
	ds_read_b64_tr_b16 v[238:239], v72 offset:28192
	ds_read_b64_tr_b16 v[240:241], v72 offset:25664
	ds_read_b64_tr_b16 v[242:243], v72 offset:28224
	s_waitcnt lgkmcnt(12)
	v_mfma_f32_16x16x32_bf16 v[34:37], v[216:219], v[180:183], v[34:37]
	v_mfma_f32_16x16x32_bf16 v[20:23], v[216:219], v[184:187], v[20:23]
	ds_read_b64_tr_b16 v[244:245], v72 offset:25696
	ds_read_b64_tr_b16 v[246:247], v72 offset:28256
	s_waitcnt lgkmcnt(12)
	v_mfma_f32_16x16x32_bf16 v[42:45], v[220:223], v[180:183], v[42:45]
	v_mfma_f32_16x16x32_bf16 v[24:27], v[220:223], v[184:187], v[24:27]
	ds_read_b128 v[248:251], v71 offset:0
	s_waitcnt lgkmcnt(11)
	v_mfma_f32_16x16x32_bf16 v[56:59], v[224:227], v[180:183], v[56:59]
	v_mfma_f32_16x16x32_bf16 v[38:41], v[224:227], v[184:187], v[38:41]
	ds_read_b128 v[216:219], v71 offset:64
	s_waitcnt lgkmcnt(10)
	v_mfma_f32_16x16x32_bf16 v[60:63], v[228:231], v[180:183], v[60:63]
	v_mfma_f32_16x16x32_bf16 v[28:31], v[228:231], v[184:187], v[28:31]
	ds_read_b128 v[220:223], v71 offset:2560
	s_waitcnt lgkmcnt(9)
	v_mfma_f32_16x16x32_bf16 v[34:37], v[232:235], v[188:191], v[34:37]
	v_mfma_f32_16x16x32_bf16 v[20:23], v[232:235], v[204:207], v[20:23]
	ds_read_b128 v[224:227], v71 offset:2624
	s_waitcnt lgkmcnt(8)
	v_mfma_f32_16x16x32_bf16 v[42:45], v[236:239], v[188:191], v[42:45]
	v_mfma_f32_16x16x32_bf16 v[24:27], v[236:239], v[204:207], v[24:27]
	ds_read_b128 v[228:231], v71 offset:5120
	s_waitcnt lgkmcnt(7)
	v_mfma_f32_16x16x32_bf16 v[56:59], v[240:243], v[188:191], v[56:59]
	v_mfma_f32_16x16x32_bf16 v[38:41], v[240:243], v[204:207], v[38:41]
	ds_read_b128 v[232:235], v71 offset:5184
	s_waitcnt lgkmcnt(6)
	v_mfma_f32_16x16x32_bf16 v[60:63], v[244:247], v[188:191], v[60:63]
	v_mfma_f32_16x16x32_bf16 v[28:31], v[244:247], v[204:207], v[28:31]
	ds_read_b128 v[236:239], v71 offset:7680
	s_waitcnt lgkmcnt(6)
	v_mfma_f32_16x16x32_bf16 v[88:91], v[248:251], v[16:19], v[48:51]
	v_mfma_f32_16x16x32_bf16 v[104:107], v[248:251], v[12:15], v[52:55]
	ds_read_b128 v[240:243], v71 offset:7744
	s_waitcnt lgkmcnt(6)
	v_mfma_f32_16x16x32_bf16 v[88:91], v[216:219], v[8:11], v[88:91]
	v_mfma_f32_16x16x32_bf16 v[104:107], v[216:219], v[4:7], v[104:107]
	s_waitcnt lgkmcnt(5)
	v_mfma_f32_16x16x32_bf16 v[92:95], v[220:223], v[16:19], v[48:51]
	v_mfma_f32_16x16x32_bf16 v[168:171], v[220:223], v[12:15], v[52:55]
	s_waitcnt lgkmcnt(4)
	v_mfma_f32_16x16x32_bf16 v[92:95], v[224:227], v[8:11], v[92:95]
	v_mfma_f32_16x16x32_bf16 v[168:171], v[224:227], v[4:7], v[168:171]
	s_waitcnt lgkmcnt(3)
	v_mfma_f32_16x16x32_bf16 v[96:99], v[228:231], v[16:19], v[48:51]
	v_mfma_f32_16x16x32_bf16 v[172:175], v[228:231], v[12:15], v[52:55]
	s_waitcnt lgkmcnt(2)
	v_mfma_f32_16x16x32_bf16 v[96:99], v[232:235], v[8:11], v[96:99]
	v_mfma_f32_16x16x32_bf16 v[172:175], v[232:235], v[4:7], v[172:175]
	s_waitcnt lgkmcnt(1)
	v_mfma_f32_16x16x32_bf16 v[100:103], v[236:239], v[16:19], v[48:51]
	v_mfma_f32_16x16x32_bf16 v[176:179], v[236:239], v[12:15], v[52:55]
	s_waitcnt lgkmcnt(0)
	v_mfma_f32_16x16x32_bf16 v[100:103], v[240:243], v[8:11], v[100:103]
	v_mfma_f32_16x16x32_bf16 v[176:179], v[240:243], v[4:7], v[176:179]
	s_mov_b32 s42, s43
	s_mov_b32 s43, s51
	s_add_i32 s51, s51, 10240
	s_cmp_lg_u32 s51, 30720
	s_cselect_b32 s51, s51, 0
	s_min_u32 s8, s20, 61
	s_add_i32 s8, s8, 2
	s_mul_i32 s30, s8, 0xf8000
	s_nop 1
	v_max3_f32 v67, v88, v89, v90
	v_max3_f32 v67, v67, v91, v92
	v_max3_f32 v67, v67, v93, v94
	v_max3_f32 v67, v67, v95, v96
	v_max3_f32 v67, v67, v97, v98
	v_max3_f32 v67, v67, v99, v100
	v_max3_f32 v67, v67, v101, v102
	v_max_f32_e32 v67, v67, v103
	v_cmp_lt_f32_e32 vcc, s66, v67
	s_cbranch_vccz .Lb_nr_A_0
	v_mov_b32_e32 v68, v67
	s_nop 1
	v_permlane16_swap_b32_e32 v67, v68
	v_max_f32_e32 v67, v67, v68
	v_mov_b32_e32 v68, v67
	s_nop 1
	v_permlane32_swap_b32_e32 v67, v68
	v_max_f32_e32 v67, v67, v68
	v_cmp_lt_f32_e32 vcc, s66, v67
	s_nop 1
	v_cndmask_b32_e32 v69, 0, v67, vcc
	v_sub_f32_e32 v70, 0, v69
	v_exp_f32_e32 v70, v70
	v_sub_f32_e32 v48, v48, v69
	v_sub_f32_e32 v49, v49, v69
	v_sub_f32_e32 v50, v50, v69
	v_sub_f32_e32 v51, v51, v69
	v_mul_f32_e32 v80, v80, v70
	v_mul_f32_e32 v34, v34, v70
	v_mul_f32_e32 v35, v35, v70
	v_mul_f32_e32 v36, v36, v70
	v_mul_f32_e32 v37, v37, v70
	v_mul_f32_e32 v42, v42, v70
	v_mul_f32_e32 v43, v43, v70
	v_mul_f32_e32 v44, v44, v70
	v_mul_f32_e32 v45, v45, v70
	v_mul_f32_e32 v56, v56, v70
	v_mul_f32_e32 v57, v57, v70
	v_mul_f32_e32 v58, v58, v70
	v_mul_f32_e32 v59, v59, v70
	v_mul_f32_e32 v60, v60, v70
	v_mul_f32_e32 v61, v61, v70
	v_mul_f32_e32 v62, v62, v70
	v_mul_f32_e32 v63, v63, v70
	v_sub_f32_e32 v88, v88, v69
	v_sub_f32_e32 v89, v89, v69
	v_sub_f32_e32 v90, v90, v69
	v_sub_f32_e32 v91, v91, v69
	v_sub_f32_e32 v92, v92, v69
	v_sub_f32_e32 v93, v93, v69
	v_sub_f32_e32 v94, v94, v69
	v_sub_f32_e32 v95, v95, v69
	v_sub_f32_e32 v96, v96, v69
	v_sub_f32_e32 v97, v97, v69
	v_sub_f32_e32 v98, v98, v69
	v_sub_f32_e32 v99, v99, v69
	v_sub_f32_e32 v100, v100, v69
	v_sub_f32_e32 v101, v101, v69
	v_sub_f32_e32 v102, v102, v69
	v_sub_f32_e32 v103, v103, v69

.Lb_nr_A_1:
	v_exp_f32_e32 v104, v104
	v_exp_f32_e32 v105, v105
	v_exp_f32_e32 v106, v106
	v_exp_f32_e32 v107, v107
	v_exp_f32_e32 v168, v168
	v_exp_f32_e32 v169, v169
	v_exp_f32_e32 v170, v170
	v_exp_f32_e32 v171, v171
	v_exp_f32_e32 v172, v172
	v_exp_f32_e32 v173, v173
	v_exp_f32_e32 v174, v174
	v_exp_f32_e32 v175, v175
	v_exp_f32_e32 v176, v176
	v_exp_f32_e32 v177, v177
	v_exp_f32_e32 v178, v178
	v_exp_f32_e32 v179, v179
	s_nop 0
	v_add_f32_e32 v67, v104, v105
	v_add_f32_e32 v67, v67, v106
	v_add_f32_e32 v67, v67, v107
	v_add_f32_e32 v67, v67, v168
	v_add_f32_e32 v67, v67, v169
	v_add_f32_e32 v67, v67, v170
	v_add_f32_e32 v67, v67, v171
	v_add_f32_e32 v67, v67, v172
	v_add_f32_e32 v67, v67, v173
	v_add_f32_e32 v67, v67, v174
	v_add_f32_e32 v67, v67, v175
	v_add_f32_e32 v67, v67, v176
	v_add_f32_e32 v67, v67, v177
	v_add_f32_e32 v67, v67, v178
	v_add_f32_e32 v67, v67, v179
	v_add_f32_e32 v64, v64, v67
	v_cvt_pk_bf16_f32 v184, v104, v105
	v_cvt_pk_bf16_f32 v185, v106, v107
	v_cvt_pk_bf16_f32 v186, v168, v169
	v_cvt_pk_bf16_f32 v187, v170, v171
	v_cvt_pk_bf16_f32 v204, v172, v173
	v_cvt_pk_bf16_f32 v205, v174, v175
	v_cvt_pk_bf16_f32 v206, v176, v177
	v_cvt_pk_bf16_f32 v207, v178, v179
	s_waitcnt vmcnt(0)
	ds_write_b128 v73, v[208:211]
	ds_write_b128 v74, v[212:215] offset:20480
	s_mov_b32 s66, 0x41000000
	s_add_i32 s20, s20, 1
	s_waitcnt lgkmcnt(0)
	s_barrier
	s_cmp_lt_u32 s20, 64
	s_cbranch_scc1 .Lb_loopA
	v_add_u32_e32 v72, s42, v119
	ds_read_b64_tr_b16 v[216:217], v72 offset:20480
	ds_read_b64_tr_b16 v[218:219], v72 offset:23040
	ds_read_b64_tr_b16 v[220:221], v72 offset:20512
	ds_read_b64_tr_b16 v[222:223], v72 offset:23072
	ds_read_b64_tr_b16 v[224:225], v72 offset:20544
	ds_read_b64_tr_b16 v[226:227], v72 offset:23104
	ds_read_b64_tr_b16 v[228:229], v72 offset:20576
	ds_read_b64_tr_b16 v[230:231], v72 offset:23136
	ds_read_b64_tr_b16 v[232:233], v72 offset:25600
	ds_read_b64_tr_b16 v[234:235], v72 offset:28160
	ds_read_b64_tr_b16 v[236:237], v72 offset:25632
	ds_read_b64_tr_b16 v[238:239], v72 offset:28192
	ds_read_b64_tr_b16 v[240:241], v72 offset:25664
	ds_read_b64_tr_b16 v[242:243], v72 offset:28224
	s_waitcnt lgkmcnt(12)
	v_mfma_f32_16x16x32_bf16 v[34:37], v[216:219], v[180:183], v[34:37]
	v_mfma_f32_16x16x32_bf16 v[20:23], v[216:219], v[184:187], v[20:23]
	ds_read_b64_tr_b16 v[244:245], v72 offset:25696
	ds_read_b64_tr_b16 v[246:247], v72 offset:28256
	s_waitcnt lgkmcnt(12)
	v_mfma_f32_16x16x32_bf16 v[42:45], v[220:223], v[180:183], v[42:45]
	v_mfma_f32_16x16x32_bf16 v[24:27], v[220:223], v[184:187], v[24:27]
	s_waitcnt lgkmcnt(10)
	v_mfma_f32_16x16x32_bf16 v[56:59], v[224:227], v[180:183], v[56:59]
	v_mfma_f32_16x16x32_bf16 v[38:41], v[224:227], v[184:187], v[38:41]
	s_waitcnt lgkmcnt(8)
	v_mfma_f32_16x16x32_bf16 v[60:63], v[228:231], v[180:183], v[60:63]
	v_mfma_f32_16x16x32_bf16 v[28:31], v[228:231], v[184:187], v[28:31]
	s_waitcnt lgkmcnt(6)
	v_mfma_f32_16x16x32_bf16 v[34:37], v[232:235], v[188:191], v[34:37]
	v_mfma_f32_16x16x32_bf16 v[20:23], v[232:235], v[204:207], v[20:23]
	s_waitcnt lgkmcnt(4)
	v_mfma_f32_16x16x32_bf16 v[42:45], v[236:239], v[188:191], v[42:45]
	v_mfma_f32_16x16x32_bf16 v[24:27], v[236:239], v[204:207], v[24:27]
	s_waitcnt lgkmcnt(2)
	v_mfma_f32_16x16x32_bf16 v[56:59], v[240:243], v[188:191], v[56:59]
	v_mfma_f32_16x16x32_bf16 v[38:41], v[240:243], v[204:207], v[38:41]
	s_waitcnt lgkmcnt(0)
	v_mfma_f32_16x16x32_bf16 v[60:63], v[244:247], v[188:191], v[60:63]
	v_mfma_f32_16x16x32_bf16 v[28:31], v[244:247], v[204:207], v[28:31]
